# grid barrier: flat release poll + leader leaves without waiting for its release atomics
# baseline (speedup 1.0000x reference)
.LBB0_255:
	s_or_b64 exec, exec, s[4:5]
	s_mov_b64 s[4:5], exec
	v_mbcnt_lo_u32_b32 v1, s4, 0
	v_mbcnt_hi_u32_b32 v1, s5, v1
	v_cmp_eq_u32_e32 vcc, 0, v1
	s_and_saveexec_b64 s[6:7], vcc
	s_cbranch_execz .LBB0_257
	s_bcnt1_i32_b64 s4, s[4:5]
	v_mov_b32_e32 v1, 0x2000
	v_mov_b32_e32 v2, s4
	global_atomic_add v1, v2, s[2:3] offset:1024
